# speedup vs baseline: 1.1023x; 1.0041x over previous
.LBB0_214:
	s_and_b64 vcc, exec, s[6:7]
	s_cbranch_vccz .LBB0_221
	v_readlane_b32 s6, v253, 0
	v_readlane_b32 s7, v253, 1
	v_mov_b32_e32 v2, v124
	s_andn2_b64 vcc, exec, s[6:7]
	s_cbranch_vccnz .LBB0_221
	v_readlane_b32 s6, v255, 5
	v_readlane_b32 s7, v255, 6
	s_add_u32 s8, s6, 0x187c0000
	v_readlane_b32 s0, v255, 15
	v_readlane_b32 s10, v255, 11
	s_addc_u32 s9, s7, 0
	s_add_i32 s2, s10, s0
	s_lshl_b32 s0, s2, 11
	s_add_u32 s6, s6, s0
	v_lshlrev_b32_e32 v0, 4, v2
	v_readlane_b32 s11, v255, 12
	s_addc_u32 s7, s7, 0
	v_and_b32_e32 v0, 0x70, v0
	v_ashrrev_i32_e32 v112, 3, v2
	v_readlane_b32 s10, v255, 7
	s_waitcnt vmcnt(2)
	v_lshl_add_u64 v[4:5], s[6:7], 0, v[0:1]
	s_mov_b64 s[6:7], 0x200000
	s_movk_i32 s0, 0x90
	v_readlane_b32 s11, v255, 8
	v_lshl_add_u64 v[100:101], v[4:5], 0, s[6:7]
	v_ashrrev_i32_e32 v4, 1, v2
	v_and_b32_e32 v5, 15, v2
	v_mad_u64_u32 v[102:103], s[6:7], v112, s0, v[0:1]
	v_and_b32_e32 v3, 64, v2
	v_lshl_add_u64 v[98:99], s[10:11], 0, v[0:1]
	v_and_or_b32 v113, v4, s67, v5
	v_lshrrev_b32_e32 v6, 2, v2
	s_lshl_b64 s[6:7], s[2:3], 11
	v_readlane_b32 s10, v255, 3
	v_and_or_b32 v114, v6, 12, v3
	v_mul_lo_u32 v3, v113, s0
	v_readlane_b32 s11, v255, 4
	s_add_u32 s0, s10, s6
	v_readlane_b32 s12, v254, 29
	s_addc_u32 s2, s11, s7
	v_readlane_b32 s14, v254, 31
	v_and_b32_e32 v0, 7, v2
	v_readlane_b32 s15, v254, 32
	s_add_u32 s6, s14, s0
	v_lshlrev_b32_e32 v0, 4, v0
	s_addc_u32 s7, s15, s2
	v_and_b32_e32 v5, 0x4f, v2
	v_lshl_add_u64 v[104:105], s[6:7], 0, v[0:1]
	s_add_u32 s6, s14, s10
	v_and_b32_e32 v4, 48, v2
	v_mul_u32_u24_e32 v5, 0x90, v5
	v_readlane_b32 s0, v254, 16
	s_addc_u32 s7, s15, s11
	v_lshl_add_u64 v[106:107], s[6:7], 0, v[0:1]
	v_add_u32_e32 v103, s0, v112
	v_add_u32_e32 v0, v4, v3
	v_add_u32_e32 v115, v4, v5
	v_and_b32_e32 v3, 7, v2
	v_and_b32_e32 v4, 7, v112
	v_xor_b32_e32 v4, v4, v3
	v_lshlrev_b32_e32 v4, 4, v4
	v_lshl_or_b32 v102, v112, 7, v4
	v_lshlrev_b32_e32 v3, 4, v3
	v_and_b32_e32 v4, 48, v2
	v_xor_b32_e32 v3, v4, v3
	v_and_b32_e32 v5, 0x4f, v2
	v_lshl_or_b32 v0, v113, 7, v3
	v_lshl_or_b32 v115, v5, 7, v3
	v_xor_b32_e32 v248, 64, v0
	v_xor_b32_e32 v249, 64, v115
	s_mov_b32 s0, s84
	v_readlane_b32 s13, v254, 30

.LBB0_218:
	s_barrier
	s_waitcnt vmcnt(7)
	ds_write_b128 v102, v[66:69]
	s_waitcnt vmcnt(6)
	ds_write_b128 v102, v[70:73] offset:18432
	s_waitcnt vmcnt(5)
	ds_write_b128 v102, v[74:77] offset:4096
	s_waitcnt vmcnt(4)
	ds_write_b128 v102, v[78:81] offset:22528
	s_waitcnt vmcnt(3)
	ds_write_b128 v102, v[82:85] offset:8192
	s_waitcnt vmcnt(2)
	ds_write_b128 v102, v[86:89] offset:26624
	s_waitcnt vmcnt(1)
	ds_write_b128 v102, v[90:93] offset:12288
	s_waitcnt vmcnt(0)
	ds_write_b128 v102, v[94:97] offset:30720
	s_waitcnt lgkmcnt(0)
	s_barrier
	s_add_u32 s100, s6, 0x27c0000
	s_addc_u32 s101, s7, 0
	v_lshl_add_u64 v[212:213], v[110:111], 0, s[100:101]
	global_load_dwordx4 v[66:69], v[212:213], off offset:128
	s_add_u32 s100, s6, 0x200000
	s_addc_u32 s101, s7, 0
	v_lshl_add_u64 v[214:215], v[108:109], 0, s[100:101]
	global_load_dwordx4 v[70:73], v[214:215], off offset:128
	s_add_u32 s100, s6, 0x27d0000
	s_addc_u32 s101, s7, 0
	v_lshl_add_u64 v[216:217], v[110:111], 0, s[100:101]
	global_load_dwordx4 v[74:77], v[216:217], off offset:128
	s_add_u32 s100, s6, 0x210000
	s_addc_u32 s101, s7, 0
	v_lshl_add_u64 v[218:219], v[108:109], 0, s[100:101]
	global_load_dwordx4 v[78:81], v[218:219], off offset:128
	s_add_u32 s100, s6, 0x27e0000
	s_addc_u32 s101, s7, 0
	v_lshl_add_u64 v[212:213], v[110:111], 0, s[100:101]
	global_load_dwordx4 v[82:85], v[212:213], off offset:128
	s_add_u32 s100, s6, 0x220000
	s_addc_u32 s101, s7, 0
	v_lshl_add_u64 v[214:215], v[108:109], 0, s[100:101]
	global_load_dwordx4 v[86:89], v[214:215], off offset:128
	s_add_u32 s100, s6, 0x27f0000
	s_addc_u32 s101, s7, 0
	v_lshl_add_u64 v[216:217], v[110:111], 0, s[100:101]
	global_load_dwordx4 v[90:93], v[216:217], off offset:128
	s_add_u32 s100, s6, 0x230000
	s_addc_u32 s101, s7, 0
	v_lshl_add_u64 v[218:219], v[108:109], 0, s[100:101]
	global_load_dwordx4 v[94:97], v[218:219], off offset:128
	ds_read_b128 v[146:149], v115 offset:18432
	ds_read_b128 v[150:153], v0
	ds_read_b128 v[154:157], v115 offset:20480
	ds_read_b128 v[158:161], v115 offset:22528
	ds_read_b128 v[162:165], v115 offset:24576
	s_waitcnt lgkmcnt(3)
	v_mfma_f32_16x16x32_bf16 v[10:13], v[146:149], v[150:153], v[10:13]
	s_waitcnt lgkmcnt(2)
	v_mfma_f32_16x16x32_bf16 v[2:5], v[154:157], v[150:153], v[2:5]
	s_waitcnt lgkmcnt(1)
	v_mfma_f32_16x16x32_bf16 v[6:9], v[158:161], v[150:153], v[6:9]
	s_waitcnt lgkmcnt(0)
	v_mfma_f32_16x16x32_bf16 v[22:25], v[162:165], v[150:153], v[22:25]
	ds_read_b128 v[150:153], v0 offset:2048
	s_waitcnt lgkmcnt(0)
	v_mfma_f32_16x16x32_bf16 v[14:17], v[146:149], v[150:153], v[14:17]
	v_mfma_f32_16x16x32_bf16 v[18:21], v[154:157], v[150:153], v[18:21]
	v_mfma_f32_16x16x32_bf16 v[26:29], v[158:161], v[150:153], v[26:29]
	v_mfma_f32_16x16x32_bf16 v[30:33], v[162:165], v[150:153], v[30:33]
	ds_read_b128 v[150:153], v0 offset:4096
	s_waitcnt lgkmcnt(0)
	v_mfma_f32_16x16x32_bf16 v[46:49], v[146:149], v[150:153], v[46:49]
	v_mfma_f32_16x16x32_bf16 v[54:57], v[154:157], v[150:153], v[54:57]
	v_mfma_f32_16x16x32_bf16 v[58:61], v[158:161], v[150:153], v[58:61]
	v_mfma_f32_16x16x32_bf16 v[62:65], v[162:165], v[150:153], v[62:65]
	ds_read_b128 v[150:153], v0 offset:6144
	s_waitcnt lgkmcnt(0)
	v_mfma_f32_16x16x32_bf16 v[50:53], v[146:149], v[150:153], v[50:53]
	v_mfma_f32_16x16x32_bf16 v[42:45], v[154:157], v[150:153], v[42:45]
	ds_read_b128 v[154:157], v249 offset:18432
	ds_read_b128 v[146:149], v248
	ds_read_b128 v[208:211], v249 offset:22528
	v_mfma_f32_16x16x32_bf16 v[34:37], v[162:165], v[150:153], v[34:37]
	ds_read_b128 v[162:165], v249 offset:20480
	v_mfma_f32_16x16x32_bf16 v[38:41], v[158:161], v[150:153], v[38:41]
	ds_read_b128 v[116:119], v249 offset:24576
	ds_read_b128 v[150:153], v248 offset:2048
	ds_read_b128 v[158:161], v248 offset:4096
	ds_read_b128 v[120:123], v248 offset:6144
	s_waitcnt lgkmcnt(6)
	v_mfma_f32_16x16x32_bf16 v[10:13], v[154:157], v[146:149], v[10:13]
	s_waitcnt lgkmcnt(4)
	v_mfma_f32_16x16x32_bf16 v[2:5], v[162:165], v[146:149], v[2:5]
	v_mfma_f32_16x16x32_bf16 v[6:9], v[208:211], v[146:149], v[6:9]
	s_waitcnt lgkmcnt(3)
	v_mfma_f32_16x16x32_bf16 v[22:25], v[116:119], v[146:149], v[22:25]
	s_waitcnt lgkmcnt(2)
	v_mfma_f32_16x16x32_bf16 v[14:17], v[154:157], v[150:153], v[14:17]
	v_mfma_f32_16x16x32_bf16 v[18:21], v[162:165], v[150:153], v[18:21]
	v_mfma_f32_16x16x32_bf16 v[26:29], v[208:211], v[150:153], v[26:29]
	v_mfma_f32_16x16x32_bf16 v[30:33], v[116:119], v[150:153], v[30:33]
	s_waitcnt lgkmcnt(1)
	v_mfma_f32_16x16x32_bf16 v[46:49], v[154:157], v[158:161], v[46:49]
	v_mfma_f32_16x16x32_bf16 v[54:57], v[162:165], v[158:161], v[54:57]
	v_mfma_f32_16x16x32_bf16 v[58:61], v[208:211], v[158:161], v[58:61]
	v_mfma_f32_16x16x32_bf16 v[62:65], v[116:119], v[158:161], v[62:65]
	s_waitcnt lgkmcnt(0)
	v_mfma_f32_16x16x32_bf16 v[50:53], v[154:157], v[120:123], v[50:53]
	v_mfma_f32_16x16x32_bf16 v[42:45], v[162:165], v[120:123], v[42:45]
	v_mfma_f32_16x16x32_bf16 v[38:41], v[208:211], v[120:123], v[38:41]
	v_mfma_f32_16x16x32_bf16 v[34:37], v[116:119], v[120:123], v[34:37]
	s_add_u32 s6, s6, 0x80
	s_addc_u32 s7, s7, 0
	s_cmpk_eq_i32 s6, 0x780
	s_cbranch_scc0 .LBB0_218
	s_barrier
	s_waitcnt vmcnt(7)
	ds_write_b128 v102, v[66:69]
	s_waitcnt vmcnt(6)
	ds_write_b128 v102, v[70:73] offset:18432
	s_waitcnt vmcnt(5)
	ds_write_b128 v102, v[74:77] offset:4096
	s_waitcnt vmcnt(4)
	ds_write_b128 v102, v[78:81] offset:22528
	s_waitcnt vmcnt(3)
	ds_write_b128 v102, v[82:85] offset:8192
	s_waitcnt vmcnt(2)
	ds_write_b128 v102, v[86:89] offset:26624
	s_waitcnt vmcnt(1)
	ds_write_b128 v102, v[90:93] offset:12288
	s_waitcnt vmcnt(0)
	ds_write_b128 v102, v[94:97] offset:30720
	s_waitcnt lgkmcnt(0)
	s_barrier
	ds_read_b128 v[66:69], v0
	ds_read_b128 v[70:73], v0 offset:2048
	ds_read_b128 v[74:77], v0 offset:4096
	ds_read_b128 v[78:81], v0 offset:6144
	ds_read_b128 v[82:85], v115 offset:18432
	ds_read_b128 v[86:89], v115 offset:20480
	ds_read_b128 v[90:93], v115 offset:22528
	ds_read_b128 v[94:97], v115 offset:24576
	s_waitcnt lgkmcnt(3)
	v_mfma_f32_16x16x32_bf16 v[10:13], v[82:85], v[66:69], v[10:13]
	s_add_i32 s0, s0, s66
	s_cmpk_gt_i32 s0, 0x3ff
	s_waitcnt lgkmcnt(2)
	v_mfma_f32_16x16x32_bf16 v[2:5], v[86:89], v[66:69], v[2:5]
	s_waitcnt lgkmcnt(1)
	v_mfma_f32_16x16x32_bf16 v[6:9], v[90:93], v[66:69], v[6:9]
	s_waitcnt lgkmcnt(0)
	v_mfma_f32_16x16x32_bf16 v[22:25], v[94:97], v[66:69], v[22:25]
	v_mfma_f32_16x16x32_bf16 v[14:17], v[82:85], v[70:73], v[14:17]
	v_mfma_f32_16x16x32_bf16 v[18:21], v[86:89], v[70:73], v[18:21]
	v_mfma_f32_16x16x32_bf16 v[26:29], v[90:93], v[70:73], v[26:29]
	v_mfma_f32_16x16x32_bf16 v[30:33], v[94:97], v[70:73], v[30:33]
	v_mfma_f32_16x16x32_bf16 v[46:49], v[82:85], v[74:77], v[46:49]
	v_mfma_f32_16x16x32_bf16 v[54:57], v[86:89], v[74:77], v[54:57]
	v_mfma_f32_16x16x32_bf16 v[58:61], v[90:93], v[74:77], v[58:61]
	v_mfma_f32_16x16x32_bf16 v[62:65], v[94:97], v[74:77], v[62:65]
	v_mfma_f32_16x16x32_bf16 v[50:53], v[82:85], v[78:81], v[50:53]
	v_mfma_f32_16x16x32_bf16 v[42:45], v[86:89], v[78:81], v[42:45]
	v_mfma_f32_16x16x32_bf16 v[38:41], v[90:93], v[78:81], v[38:41]
	v_mfma_f32_16x16x32_bf16 v[34:37], v[94:97], v[78:81], v[34:37]
	ds_read_b128 v[66:69], v248
	ds_read_b128 v[70:73], v248 offset:2048
	ds_read_b128 v[74:77], v248 offset:4096
	ds_read_b128 v[78:81], v248 offset:6144
	ds_read_b128 v[82:85], v249 offset:18432
	ds_read_b128 v[86:89], v249 offset:20480
	ds_read_b128 v[90:93], v249 offset:22528
	ds_read_b128 v[94:97], v249 offset:24576
	s_waitcnt lgkmcnt(3)
	v_mfma_f32_16x16x32_bf16 v[10:13], v[82:85], v[66:69], v[10:13]
	s_waitcnt lgkmcnt(2)
	v_mfma_f32_16x16x32_bf16 v[2:5], v[86:89], v[66:69], v[2:5]
	s_waitcnt lgkmcnt(1)
	v_mfma_f32_16x16x32_bf16 v[6:9], v[90:93], v[66:69], v[6:9]
	s_waitcnt lgkmcnt(0)
	v_mfma_f32_16x16x32_bf16 v[22:25], v[94:97], v[66:69], v[22:25]
	v_add_u32_e32 v66, s2, v113
	v_or_b32_e32 v68, s26, v114
	v_ashrrev_i32_e32 v67, 31, v66
	v_mfma_f32_16x16x32_bf16 v[14:17], v[82:85], v[70:73], v[14:17]
	v_ashrrev_i32_e32 v69, 31, v68
	v_lshlrev_b64 v[68:69], 2, v[68:69]
	v_readlane_b32 s2, v254, 17
	v_mfma_f32_16x16x32_bf16 v[18:21], v[86:89], v[70:73], v[18:21]
	s_nop 0
	v_add_u32_e32 v103, s2, v103
	v_mfma_f32_16x16x32_bf16 v[26:29], v[90:93], v[70:73], v[26:29]
	v_mfma_f32_16x16x32_bf16 v[30:33], v[94:97], v[70:73], v[30:33]
	v_lshlrev_b64 v[70:71], 12, v[66:67]
	v_lshl_add_u64 v[70:71], s[8:9], 0, v[70:71]
	v_lshl_add_u64 v[70:71], v[70:71], 0, v[68:69]
	global_store_dwordx4 v[70:71], v[10:13], off
	global_store_dwordx4 v[70:71], v[2:5], off offset:64
	global_store_dwordx4 v[70:71], v[6:9], off offset:128
	global_store_dwordx4 v[70:71], v[22:25], off offset:192
	v_or_b32_e32 v2, 16, v66
	v_ashrrev_i32_e32 v3, 31, v2
	v_lshlrev_b64 v[2:3], 12, v[2:3]
	v_lshl_add_u64 v[2:3], s[8:9], 0, v[2:3]
	v_lshl_add_u64 v[2:3], v[2:3], 0, v[68:69]
	global_store_dwordx4 v[2:3], v[14:17], off
	global_store_dwordx4 v[2:3], v[18:21], off offset:64
	global_store_dwordx4 v[2:3], v[26:29], off offset:128
	global_store_dwordx4 v[2:3], v[30:33], off offset:192
	v_or_b32_e32 v2, 32, v66
	v_mfma_f32_16x16x32_bf16 v[46:49], v[82:85], v[74:77], v[46:49]
	v_ashrrev_i32_e32 v3, 31, v2
	v_lshlrev_b64 v[2:3], 12, v[2:3]
	v_lshl_add_u64 v[2:3], s[8:9], 0, v[2:3]
	v_mfma_f32_16x16x32_bf16 v[54:57], v[86:89], v[74:77], v[54:57]
	v_lshl_add_u64 v[2:3], v[2:3], 0, v[68:69]
	v_mfma_f32_16x16x32_bf16 v[58:61], v[90:93], v[74:77], v[58:61]
	v_mfma_f32_16x16x32_bf16 v[62:65], v[94:97], v[74:77], v[62:65]
	s_nop 0
	global_store_dwordx4 v[2:3], v[46:49], off
	s_nop 2
	global_store_dwordx4 v[2:3], v[54:57], off offset:64
	s_nop 0
	global_store_dwordx4 v[2:3], v[58:61], off offset:128
	global_store_dwordx4 v[2:3], v[62:65], off offset:192
	v_or_b32_e32 v2, 48, v66
	v_ashrrev_i32_e32 v3, 31, v2
	v_mfma_f32_16x16x32_bf16 v[50:53], v[82:85], v[78:81], v[50:53]
	v_lshlrev_b64 v[2:3], 12, v[2:3]
	v_lshl_add_u64 v[2:3], s[8:9], 0, v[2:3]
	v_lshl_add_u64 v[2:3], v[2:3], 0, v[68:69]
	v_mfma_f32_16x16x32_bf16 v[42:45], v[86:89], v[78:81], v[42:45]
	v_mfma_f32_16x16x32_bf16 v[38:41], v[90:93], v[78:81], v[38:41]
	v_mfma_f32_16x16x32_bf16 v[34:37], v[94:97], v[78:81], v[34:37]
	s_nop 1
	global_store_dwordx4 v[2:3], v[50:53], off
	s_nop 2
	global_store_dwordx4 v[2:3], v[42:45], off offset:64
	global_store_dwordx4 v[2:3], v[38:41], off offset:128
	global_store_dwordx4 v[2:3], v[34:37], off offset:192
	s_cbranch_scc0 .LBB0_217
	s_movk_i32 s26, 0xff

.LBB0_239:
	v_readlane_b32 s6, v253, 0
	v_readlane_b32 s7, v253, 1
	v_mov_b32_e32 v2, v124
	s_andn2_b64 vcc, exec, s[6:7]
	s_cbranch_vccnz .LBB0_245
	v_readlane_b32 s0, v255, 15
	v_readlane_b32 s6, v255, 11
	v_readlane_b32 s7, v255, 12
	s_add_i32 s2, s6, s0
	s_lshl_b32 s0, s2, 11
	v_readlane_b32 s6, v255, 5
	v_readlane_b32 s7, v255, 6
	s_add_u32 s6, s6, s0
	v_lshlrev_b32_e32 v0, 4, v2
	v_ashrrev_i32_e32 v112, 3, v2
	s_addc_u32 s7, s7, 0
	v_and_b32_e32 v0, 0x70, v0
	s_movk_i32 s0, 0x90
	v_lshl_add_u64 v[100:101], s[6:7], 0, v[0:1]
	s_waitcnt vmcnt(2)
	v_ashrrev_i32_e32 v4, 1, v2
	v_and_b32_e32 v5, 15, v2
	v_mad_u64_u32 v[102:103], s[6:7], v112, s0, v[0:1]
	v_and_b32_e32 v3, 64, v2
	v_and_or_b32 v113, v4, s67, v5
	v_lshrrev_b32_e32 v6, 2, v2
	s_lshl_b64 s[6:7], s[2:3], 11
	v_readlane_b32 s10, v255, 3
	v_and_or_b32 v114, v6, 12, v3
	v_mul_lo_u32 v3, v113, s0
	v_readlane_b32 s11, v255, 4
	s_add_u32 s0, s10, s6
	v_readlane_b32 s12, v254, 29
	s_addc_u32 s2, s11, s7
	v_readlane_b32 s14, v254, 31
	v_lshl_add_u64 v[98:99], s[24:25], 0, v[0:1]
	v_and_b32_e32 v0, 7, v2
	v_readlane_b32 s15, v254, 32
	s_add_u32 s6, s14, s0
	v_lshlrev_b32_e32 v0, 4, v0
	s_addc_u32 s7, s15, s2
	v_and_b32_e32 v5, 0x4f, v2
	v_lshl_add_u64 v[104:105], s[6:7], 0, v[0:1]
	s_add_u32 s6, s14, s10
	v_and_b32_e32 v4, 48, v2
	v_mul_u32_u24_e32 v5, 0x90, v5
	v_readlane_b32 s0, v254, 16
	s_addc_u32 s7, s15, s11
	v_lshl_add_u64 v[106:107], s[6:7], 0, v[0:1]
	v_add_u32_e32 v103, s0, v112
	v_add_u32_e32 v0, v4, v3
	v_add_u32_e32 v115, v4, v5
	v_and_b32_e32 v3, 7, v2
	v_and_b32_e32 v4, 7, v112
	v_xor_b32_e32 v4, v4, v3
	v_lshlrev_b32_e32 v4, 4, v4
	v_lshl_or_b32 v102, v112, 7, v4
	v_lshlrev_b32_e32 v3, 4, v3
	v_and_b32_e32 v4, 48, v2
	v_xor_b32_e32 v3, v4, v3
	v_and_b32_e32 v5, 0x4f, v2
	v_lshl_or_b32 v0, v113, 7, v3
	v_lshl_or_b32 v115, v5, 7, v3
	v_xor_b32_e32 v248, 64, v0
	v_xor_b32_e32 v249, 64, v115
	s_mov_b32 s2, s84
	v_readlane_b32 s13, v254, 30

.LBB0_242:
	s_waitcnt lgkmcnt(0)
	s_barrier
	s_waitcnt vmcnt(6)
	ds_write_b128 v102, v[70:73]
	s_waitcnt vmcnt(6)
	ds_write_b128 v102, v[66:69] offset:18432
	s_waitcnt vmcnt(5)
	ds_write_b128 v102, v[74:77] offset:4096
	s_waitcnt vmcnt(4)
	ds_write_b128 v102, v[78:81] offset:22528
	s_waitcnt vmcnt(3)
	ds_write_b128 v102, v[82:85] offset:8192
	s_waitcnt vmcnt(2)
	ds_write_b128 v102, v[86:89] offset:26624
	s_waitcnt vmcnt(1)
	ds_write_b128 v102, v[90:93] offset:12288
	s_waitcnt vmcnt(0)
	ds_write_b128 v102, v[94:97] offset:30720
	s_waitcnt lgkmcnt(0)
	s_barrier
	v_lshl_add_u64 v[212:213], v[108:109], 0, s[6:7]
	global_load_dwordx4 v[66:69], v[212:213], off offset:128
	s_add_u32 s100, s6, 0xa7c0000
	s_addc_u32 s101, s7, 0
	v_lshl_add_u64 v[214:215], v[110:111], 0, s[100:101]
	global_load_dwordx4 v[70:73], v[214:215], off offset:128
	s_add_u32 s100, s6, 0xa7d0000
	s_addc_u32 s101, s7, 0
	v_lshl_add_u64 v[216:217], v[110:111], 0, s[100:101]
	global_load_dwordx4 v[74:77], v[216:217], off offset:128
	s_add_u32 s100, s6, 0x10000
	s_addc_u32 s101, s7, 0
	v_lshl_add_u64 v[218:219], v[108:109], 0, s[100:101]
	global_load_dwordx4 v[78:81], v[218:219], off offset:128
	s_add_u32 s100, s6, 0xa7e0000
	s_addc_u32 s101, s7, 0
	v_lshl_add_u64 v[212:213], v[110:111], 0, s[100:101]
	global_load_dwordx4 v[82:85], v[212:213], off offset:128
	s_add_u32 s100, s6, 0x20000
	s_addc_u32 s101, s7, 0
	v_lshl_add_u64 v[214:215], v[108:109], 0, s[100:101]
	global_load_dwordx4 v[86:89], v[214:215], off offset:128
	s_add_u32 s100, s6, 0xa7f0000
	s_addc_u32 s101, s7, 0
	v_lshl_add_u64 v[216:217], v[110:111], 0, s[100:101]
	global_load_dwordx4 v[90:93], v[216:217], off offset:128
	s_add_u32 s100, s6, 0x30000
	s_addc_u32 s101, s7, 0
	v_lshl_add_u64 v[218:219], v[108:109], 0, s[100:101]
	global_load_dwordx4 v[94:97], v[218:219], off offset:128
	ds_read_b128 v[146:149], v115 offset:18432
	ds_read_b128 v[150:153], v0
	ds_read_b128 v[154:157], v115 offset:20480
	ds_read_b128 v[158:161], v115 offset:22528
	ds_read_b128 v[162:165], v115 offset:24576
	s_waitcnt lgkmcnt(3)
	v_mfma_f32_16x16x32_bf16 v[14:17], v[146:149], v[150:153], v[14:17]
	ds_read_b128 v[208:211], v249 offset:22528
	s_waitcnt lgkmcnt(3)
	v_mfma_f32_16x16x32_bf16 v[10:13], v[154:157], v[150:153], v[10:13]
	s_waitcnt lgkmcnt(2)
	v_mfma_f32_16x16x32_bf16 v[2:5], v[158:161], v[150:153], v[2:5]
	s_waitcnt lgkmcnt(1)
	v_mfma_f32_16x16x32_bf16 v[6:9], v[162:165], v[150:153], v[6:9]
	ds_read_b128 v[150:153], v0 offset:2048
	s_waitcnt lgkmcnt(0)
	v_mfma_f32_16x16x32_bf16 v[26:29], v[146:149], v[150:153], v[26:29]
	v_mfma_f32_16x16x32_bf16 v[22:25], v[154:157], v[150:153], v[22:25]
	v_mfma_f32_16x16x32_bf16 v[18:21], v[158:161], v[150:153], v[18:21]
	v_mfma_f32_16x16x32_bf16 v[30:33], v[162:165], v[150:153], v[30:33]
	ds_read_b128 v[150:153], v0 offset:4096
	s_waitcnt lgkmcnt(0)
	v_mfma_f32_16x16x32_bf16 v[34:37], v[146:149], v[150:153], v[34:37]
	v_mfma_f32_16x16x32_bf16 v[42:45], v[154:157], v[150:153], v[42:45]
	v_mfma_f32_16x16x32_bf16 v[50:53], v[158:161], v[150:153], v[50:53]
	v_mfma_f32_16x16x32_bf16 v[58:61], v[162:165], v[150:153], v[58:61]
	ds_read_b128 v[150:153], v0 offset:6144
	s_waitcnt lgkmcnt(0)
	v_mfma_f32_16x16x32_bf16 v[54:57], v[154:157], v[150:153], v[54:57]
	ds_read_b128 v[154:157], v249 offset:18432
	v_mfma_f32_16x16x32_bf16 v[38:41], v[162:165], v[150:153], v[38:41]
	ds_read_b128 v[162:165], v249 offset:20480
	v_mfma_f32_16x16x32_bf16 v[62:65], v[146:149], v[150:153], v[62:65]
	ds_read_b128 v[146:149], v248
	v_mfma_f32_16x16x32_bf16 v[46:49], v[158:161], v[150:153], v[46:49]
	ds_read_b128 v[116:119], v249 offset:24576
	ds_read_b128 v[150:153], v248 offset:2048
	ds_read_b128 v[158:161], v248 offset:4096
	ds_read_b128 v[120:123], v248 offset:6144
	s_waitcnt lgkmcnt(4)
	v_mfma_f32_16x16x32_bf16 v[14:17], v[154:157], v[146:149], v[14:17]
	v_mfma_f32_16x16x32_bf16 v[10:13], v[162:165], v[146:149], v[10:13]
	v_mfma_f32_16x16x32_bf16 v[2:5], v[208:211], v[146:149], v[2:5]
	s_waitcnt lgkmcnt(3)
	v_mfma_f32_16x16x32_bf16 v[6:9], v[116:119], v[146:149], v[6:9]
	s_waitcnt lgkmcnt(2)
	v_mfma_f32_16x16x32_bf16 v[26:29], v[154:157], v[150:153], v[26:29]
	v_mfma_f32_16x16x32_bf16 v[22:25], v[162:165], v[150:153], v[22:25]
	v_mfma_f32_16x16x32_bf16 v[18:21], v[208:211], v[150:153], v[18:21]
	v_mfma_f32_16x16x32_bf16 v[30:33], v[116:119], v[150:153], v[30:33]
	s_waitcnt lgkmcnt(1)
	v_mfma_f32_16x16x32_bf16 v[34:37], v[154:157], v[158:161], v[34:37]
	v_mfma_f32_16x16x32_bf16 v[42:45], v[162:165], v[158:161], v[42:45]
	v_mfma_f32_16x16x32_bf16 v[50:53], v[208:211], v[158:161], v[50:53]
	v_mfma_f32_16x16x32_bf16 v[58:61], v[116:119], v[158:161], v[58:61]
	s_waitcnt lgkmcnt(0)
	v_mfma_f32_16x16x32_bf16 v[62:65], v[154:157], v[120:123], v[62:65]
	v_mfma_f32_16x16x32_bf16 v[54:57], v[162:165], v[120:123], v[54:57]
	v_mfma_f32_16x16x32_bf16 v[46:49], v[208:211], v[120:123], v[46:49]
	v_mfma_f32_16x16x32_bf16 v[38:41], v[116:119], v[120:123], v[38:41]
	s_add_u32 s6, s6, 0x80
	s_addc_u32 s7, s7, 0
	s_cmpk_eq_i32 s6, 0x780
	s_cbranch_scc0 .LBB0_242
	s_barrier
	s_waitcnt vmcnt(6)
	ds_write_b128 v102, v[70:73]
	ds_write_b128 v102, v[66:69] offset:18432
	s_waitcnt vmcnt(5)
	ds_write_b128 v102, v[74:77] offset:4096
	s_waitcnt vmcnt(4)
	ds_write_b128 v102, v[78:81] offset:22528
	s_waitcnt vmcnt(3)
	ds_write_b128 v102, v[82:85] offset:8192
	s_waitcnt vmcnt(2)
	ds_write_b128 v102, v[86:89] offset:26624
	s_waitcnt vmcnt(1)
	ds_write_b128 v102, v[90:93] offset:12288
	s_waitcnt vmcnt(0)
	ds_write_b128 v102, v[94:97] offset:30720
	s_waitcnt lgkmcnt(0)
	s_barrier
	ds_read_b128 v[66:69], v0
	ds_read_b128 v[70:73], v0 offset:2048
	ds_read_b128 v[74:77], v0 offset:4096
	ds_read_b128 v[78:81], v0 offset:6144
	ds_read_b128 v[82:85], v115 offset:18432
	ds_read_b128 v[86:89], v115 offset:20480
	ds_read_b128 v[90:93], v115 offset:22528
	ds_read_b128 v[94:97], v115 offset:24576
	s_waitcnt lgkmcnt(3)
	v_mfma_f32_16x16x32_bf16 v[14:17], v[82:85], v[66:69], v[14:17]
	s_add_i32 s2, s2, s66
	s_cmpk_gt_i32 s2, 0x3ff
	s_waitcnt lgkmcnt(2)
	v_mfma_f32_16x16x32_bf16 v[10:13], v[86:89], v[66:69], v[10:13]
	s_waitcnt lgkmcnt(1)
	v_mfma_f32_16x16x32_bf16 v[2:5], v[90:93], v[66:69], v[2:5]
	s_waitcnt lgkmcnt(0)
	v_mfma_f32_16x16x32_bf16 v[6:9], v[94:97], v[66:69], v[6:9]
	v_mfma_f32_16x16x32_bf16 v[26:29], v[82:85], v[70:73], v[26:29]
	v_mfma_f32_16x16x32_bf16 v[22:25], v[86:89], v[70:73], v[22:25]
	v_mfma_f32_16x16x32_bf16 v[18:21], v[90:93], v[70:73], v[18:21]
	v_mfma_f32_16x16x32_bf16 v[30:33], v[94:97], v[70:73], v[30:33]
	v_mfma_f32_16x16x32_bf16 v[66:69], v[82:85], v[74:77], v[34:37]
	v_mfma_f32_16x16x32_bf16 v[70:73], v[86:89], v[74:77], v[42:45]
	v_mfma_f32_16x16x32_bf16 v[50:53], v[90:93], v[74:77], v[50:53]
	v_mfma_f32_16x16x32_bf16 v[58:61], v[94:97], v[74:77], v[58:61]
	v_mfma_f32_16x16x32_bf16 v[62:65], v[82:85], v[78:81], v[62:65]
	v_mfma_f32_16x16x32_bf16 v[54:57], v[86:89], v[78:81], v[54:57]
	v_mfma_f32_16x16x32_bf16 v[74:77], v[90:93], v[78:81], v[46:49]
	v_mfma_f32_16x16x32_bf16 v[78:81], v[94:97], v[78:81], v[38:41]
	ds_read_b128 v[34:37], v248
	ds_read_b128 v[82:85], v248 offset:2048
	ds_read_b128 v[86:89], v248 offset:4096
	ds_read_b128 v[90:93], v248 offset:6144
	ds_read_b128 v[94:97], v249 offset:18432
	ds_read_b128 v[108:111], v249 offset:20480
	ds_read_b128 v[116:119], v249 offset:22528
	ds_read_b128 v[120:123], v249 offset:24576
	s_waitcnt lgkmcnt(2)
	v_mfma_f32_16x16x32_bf16 v[42:45], v[108:111], v[82:85], v[22:25]
	s_waitcnt lgkmcnt(1)
	v_mfma_f32_16x16x32_bf16 v[22:25], v[116:119], v[86:89], v[50:53]
	s_nop 2
	v_add_u32_e32 v50, s0, v113
	v_or_b32_e32 v52, s26, v114
	v_ashrrev_i32_e32 v51, 31, v50
	v_mfma_f32_16x16x32_bf16 v[130:133], v[108:111], v[34:37], v[10:13]
	v_ashrrev_i32_e32 v53, 31, v52
	v_lshlrev_b64 v[52:53], 2, v[52:53]
	v_readlane_b32 s0, v254, 17
	v_mfma_f32_16x16x32_bf16 v[10:13], v[108:111], v[90:93], v[54:57]
	s_nop 0
	v_add_u32_e32 v103, s0, v103
	s_nop 0
	v_lshlrev_b64 v[54:55], 12, v[50:51]
	v_lshl_add_u64 v[56:57], s[22:23], 0, v[54:55]
	v_mfma_f32_16x16x32_bf16 v[38:41], v[116:119], v[82:85], v[18:21]
	v_lshl_add_u64 v[54:55], s[8:9], 0, v[54:55]
	s_waitcnt lgkmcnt(0)
	v_mfma_f32_16x16x32_bf16 v[18:21], v[120:123], v[86:89], v[58:61]
	s_nop 2
	v_lshl_add_u64 v[58:59], v[56:57], 0, v[52:53]
	v_lshl_add_u64 v[60:61], v[54:55], 0, v[52:53]
	global_load_dwordx4 v[54:57], v[58:59], off
	v_mfma_f32_16x16x32_bf16 v[126:129], v[94:97], v[34:37], v[14:17]
	v_mfma_f32_16x16x32_bf16 v[134:137], v[116:119], v[34:37], v[2:5]
	v_mfma_f32_16x16x32_bf16 v[138:141], v[120:123], v[34:37], v[6:9]
	s_waitcnt vmcnt(0)
	s_nop 4
	v_pk_add_f32 v[54:55], v[126:127], v[54:55]
	v_pk_add_f32 v[56:57], v[128:129], v[56:57]
	global_store_dwordx4 v[60:61], v[54:57], off
	global_load_dwordx4 v[54:57], v[58:59], off offset:64
	v_mfma_f32_16x16x32_bf16 v[46:49], v[94:97], v[82:85], v[26:29]
	s_waitcnt vmcnt(0)
	v_pk_add_f32 v[54:55], v[130:131], v[54:55]
	v_pk_add_f32 v[56:57], v[132:133], v[56:57]
	global_store_dwordx4 v[60:61], v[54:57], off offset:64
	global_load_dwordx4 v[54:57], v[58:59], off offset:128
	v_mfma_f32_16x16x32_bf16 v[34:37], v[120:123], v[82:85], v[30:33]
	s_waitcnt vmcnt(0)
	v_pk_add_f32 v[54:55], v[134:135], v[54:55]
	v_pk_add_f32 v[56:57], v[136:137], v[56:57]
	global_store_dwordx4 v[60:61], v[54:57], off offset:128
	global_load_dwordx4 v[54:57], v[58:59], off offset:192
	v_mfma_f32_16x16x32_bf16 v[30:33], v[94:97], v[86:89], v[66:69]
	s_waitcnt vmcnt(0)
	v_pk_add_f32 v[54:55], v[138:139], v[54:55]
	v_pk_add_f32 v[56:57], v[140:141], v[56:57]
	global_store_dwordx4 v[60:61], v[54:57], off offset:192
	v_mfma_f32_16x16x32_bf16 v[26:29], v[108:111], v[86:89], v[70:73]
	s_nop 0
	v_or_b32_e32 v54, 16, v50
	v_ashrrev_i32_e32 v55, 31, v54
	v_lshlrev_b64 v[54:55], 12, v[54:55]
	v_lshl_add_u64 v[56:57], s[22:23], 0, v[54:55]
	v_lshl_add_u64 v[54:55], s[8:9], 0, v[54:55]
	v_lshl_add_u64 v[58:59], v[56:57], 0, v[52:53]
	v_lshl_add_u64 v[60:61], v[54:55], 0, v[52:53]
	global_load_dwordx4 v[54:57], v[58:59], off
	v_mfma_f32_16x16x32_bf16 v[14:17], v[94:97], v[90:93], v[62:65]
	s_waitcnt vmcnt(0)
	v_pk_add_f32 v[46:47], v[46:47], v[54:55]
	v_pk_add_f32 v[48:49], v[48:49], v[56:57]
	global_store_dwordx4 v[60:61], v[46:49], off
	global_load_dwordx4 v[46:49], v[58:59], off offset:64
	v_mfma_f32_16x16x32_bf16 v[6:9], v[116:119], v[90:93], v[74:77]
	s_waitcnt vmcnt(0)
	v_pk_add_f32 v[42:43], v[42:43], v[46:47]
	v_pk_add_f32 v[44:45], v[44:45], v[48:49]
	global_store_dwordx4 v[60:61], v[42:45], off offset:64
	global_load_dwordx4 v[42:45], v[58:59], off offset:128
	v_mfma_f32_16x16x32_bf16 v[2:5], v[120:123], v[90:93], v[78:81]
	s_waitcnt vmcnt(0)
	v_pk_add_f32 v[38:39], v[38:39], v[42:43]
	v_pk_add_f32 v[40:41], v[40:41], v[44:45]
	global_store_dwordx4 v[60:61], v[38:41], off offset:128
	global_load_dwordx4 v[38:41], v[58:59], off offset:192
	s_waitcnt vmcnt(0)
	v_pk_add_f32 v[34:35], v[34:35], v[38:39]
	v_pk_add_f32 v[36:37], v[36:37], v[40:41]
	global_store_dwordx4 v[60:61], v[34:37], off offset:192
	s_nop 1
	v_or_b32_e32 v34, 32, v50
	v_ashrrev_i32_e32 v35, 31, v34
	v_lshlrev_b64 v[34:35], 12, v[34:35]
	v_lshl_add_u64 v[36:37], s[22:23], 0, v[34:35]
	v_lshl_add_u64 v[34:35], s[8:9], 0, v[34:35]
	v_lshl_add_u64 v[38:39], v[36:37], 0, v[52:53]
	v_lshl_add_u64 v[40:41], v[34:35], 0, v[52:53]
	global_load_dwordx4 v[34:37], v[38:39], off
	s_waitcnt vmcnt(0)
	v_pk_add_f32 v[30:31], v[30:31], v[34:35]
	v_pk_add_f32 v[32:33], v[32:33], v[36:37]
	global_store_dwordx4 v[40:41], v[30:33], off
	global_load_dwordx4 v[30:33], v[38:39], off offset:64
	s_waitcnt vmcnt(0)
	v_pk_add_f32 v[26:27], v[26:27], v[30:31]
	v_pk_add_f32 v[28:29], v[28:29], v[32:33]
	global_store_dwordx4 v[40:41], v[26:29], off offset:64
	global_load_dwordx4 v[26:29], v[38:39], off offset:128
	s_waitcnt vmcnt(0)
	v_pk_add_f32 v[22:23], v[22:23], v[26:27]
	v_pk_add_f32 v[24:25], v[24:25], v[28:29]
	global_store_dwordx4 v[40:41], v[22:25], off offset:128
	global_load_dwordx4 v[22:25], v[38:39], off offset:192
	s_waitcnt vmcnt(0)
	v_pk_add_f32 v[18:19], v[18:19], v[22:23]
	v_pk_add_f32 v[20:21], v[20:21], v[24:25]
	global_store_dwordx4 v[40:41], v[18:21], off offset:192
	s_nop 1
	v_or_b32_e32 v18, 48, v50
	v_ashrrev_i32_e32 v19, 31, v18
	v_lshlrev_b64 v[18:19], 12, v[18:19]
	v_lshl_add_u64 v[20:21], s[22:23], 0, v[18:19]
	v_lshl_add_u64 v[24:25], v[20:21], 0, v[52:53]
	global_load_dwordx4 v[20:23], v[24:25], off
	v_lshl_add_u64 v[18:19], s[8:9], 0, v[18:19]
	v_lshl_add_u64 v[18:19], v[18:19], 0, v[52:53]
	s_waitcnt vmcnt(0)
	v_pk_add_f32 v[14:15], v[14:15], v[20:21]
	v_pk_add_f32 v[16:17], v[16:17], v[22:23]
	global_store_dwordx4 v[18:19], v[14:17], off
	global_load_dwordx4 v[14:17], v[24:25], off offset:64
	s_waitcnt vmcnt(0)
	v_pk_add_f32 v[10:11], v[10:11], v[14:15]
	v_pk_add_f32 v[12:13], v[12:13], v[16:17]
	global_store_dwordx4 v[18:19], v[10:13], off offset:64
	global_load_dwordx4 v[10:13], v[24:25], off offset:128
	s_waitcnt vmcnt(0)
	v_pk_add_f32 v[6:7], v[6:7], v[10:11]
	v_pk_add_f32 v[8:9], v[8:9], v[12:13]
	global_store_dwordx4 v[18:19], v[6:9], off offset:128
	global_load_dwordx4 v[6:9], v[24:25], off offset:192
	s_waitcnt vmcnt(0)
	v_pk_add_f32 v[2:3], v[2:3], v[6:7]
	v_pk_add_f32 v[4:5], v[4:5], v[8:9]
	global_store_dwordx4 v[18:19], v[2:5], off offset:192
	s_cbranch_scc0 .LBB0_241
	s_movk_i32 s26, 0xff

.LBB0_786:
	s_andn2_b64 vcc, exec, s[6:7]
	v_readlane_b32 s16, v254, 52
	s_cbranch_vccnz .LBB0_844
	v_readlane_b32 s0, v255, 18
	s_cmp_eq_u32 s0, 1
	s_mov_b64 s[6:7], -1
	s_cbranch_scc1 .LBB0_808
	v_readlane_b32 s17, v255, 15
	v_readlane_b32 s10, v255, 7
	s_waitcnt lgkmcnt(0)
	v_readlane_b32 s22, v255, 19
	v_mov_b32_e32 v2, v124
	s_cmp_ge_i32 s84, s17
	s_movk_i32 s8, 0xffc0
	s_mov_b32 s15, 0x27d0000
	v_readlane_b32 s11, v255, 8
	v_readlane_b32 s20, v255, 16
	v_readlane_b32 s23, v255, 20
	s_cbranch_scc1 .LBB0_807
	s_lshr_b32 s2, s17, 7
	v_readlane_b32 s18, v255, 11
	s_lshl_b32 s0, s18, 11
	v_readlane_b32 s12, v255, 5
	s_waitcnt vmcnt(2)
	v_ashrrev_i32_e32 v4, 1, v2
	v_and_b32_e32 v5, 15, v2
	v_cvt_f32_ubyte0_e32 v8, s2
	v_readlane_b32 s13, v255, 6
	s_add_u32 s6, s12, s0
	v_lshlrev_b32_e32 v0, 4, v2
	v_and_or_b32 v118, v4, s8, v5
	v_lshrrev_b32_e32 v4, 2, v2
	v_rcp_iflag_f32_e32 v8, v8
	s_addc_u32 s7, s13, 0
	v_and_b32_e32 v0, 0x70, v0
	v_and_b32_e32 v119, 12, v4
	v_and_b32_e32 v4, 16, v2
	v_mov_b32_e32 v5, v1
	v_lshl_add_u64 v[100:101], s[6:7], 0, v[0:1]
	v_lshl_add_u64 v[4:5], s[12:13], 0, v[4:5]
	s_mov_b64 s[6:7], 0x2740000
	v_lshl_add_u64 v[102:103], v[4:5], 0, s[6:7]
	s_mov_b64 s[6:7], 0x2780000
	v_lshl_add_u64 v[104:105], v[4:5], 0, s[6:7]
	v_mul_f32_e32 v4, 0x4f7ffffe, v8
	v_cvt_u32_f32_e32 v4, v4
	v_ashrrev_i32_e32 v116, 3, v2
	s_movk_i32 s0, 0x90
	v_and_b32_e32 v3, 32, v2
	v_mad_u64_u32 v[106:107], s[6:7], v116, s0, v[0:1]
	v_cmp_eq_u32_e64 s[44:45], 0, v3
	v_mul_lo_u32 v3, v118, s0
	s_sub_i32 s0, 0, s2
	v_readfirstlane_b32 s6, v4
	v_readlane_b32 s19, v255, 12
	s_mul_i32 s0, s0, s6
	s_mul_hi_u32 s0, s6, s0
	s_mov_b32 s19, s3
	s_add_i32 s12, s6, s0
	s_lshl_b64 s[6:7], s[18:19], 11
	v_readlane_b32 s18, v255, 3
	v_lshl_add_u64 v[98:99], s[10:11], 0, v[0:1]
	v_readlane_b32 s19, v255, 4
	s_add_u32 s0, s18, s6
	v_readlane_b32 s8, v254, 29
	s_addc_u32 s7, s19, s7
	v_readlane_b32 s10, v254, 31
	v_and_b32_e32 v0, 7, v2
	v_readlane_b32 s11, v254, 32
	s_add_u32 s6, s10, s0
	v_lshlrev_b32_e32 v0, 4, v0
	s_addc_u32 s7, s11, s7
	s_and_b32 s13, s17, 0xf80
	v_and_b32_e32 v7, 0x4f, v2
	v_lshl_add_u64 v[108:109], s[6:7], 0, v[0:1]
	s_add_u32 s6, s10, s18
	v_and_b32_e32 v6, 48, v2
	v_mul_u32_u24_e32 v5, 0x90, v7
	v_readlane_b32 s0, v254, 16
	s_addc_u32 s7, s11, s19
	v_and_b32_e32 v117, 64, v2
	v_add_u32_e32 v107, s0, v116
	v_lshl_add_u64 v[110:111], s[6:7], 0, v[0:1]
	v_add_u32_e32 v120, v6, v3
	v_add_u32_e32 v121, v6, v5
	v_and_b32_e32 v3, 7, v2
	v_and_b32_e32 v4, 7, v116
	v_xor_b32_e32 v4, v4, v3
	v_lshlrev_b32_e32 v4, 4, v4
	v_lshl_or_b32 v106, v116, 7, v4
	v_lshlrev_b32_e32 v3, 4, v3
	v_and_b32_e32 v4, 48, v2
	v_xor_b32_e32 v3, v4, v3
	v_lshl_or_b32 v120, v118, 7, v3
	v_lshl_or_b32 v121, v7, 7, v3
	v_xor_b32_e32 v248, 64, v120
	v_xor_b32_e32 v249, 64, v121
	s_mov_b32 s14, s84
	v_readlane_b32 s9, v254, 30
	s_branch .LBB0_791

.LBB0_792:
	s_barrier
	s_waitcnt vmcnt(7)
	ds_write_b128 v106, v[66:69]
	s_waitcnt vmcnt(6)
	ds_write_b128 v106, v[70:73] offset:18432
	s_waitcnt vmcnt(5)
	ds_write_b128 v106, v[74:77] offset:4096
	s_waitcnt vmcnt(4)
	ds_write_b128 v106, v[78:81] offset:22528
	s_waitcnt vmcnt(3)
	ds_write_b128 v106, v[82:85] offset:8192
	s_waitcnt vmcnt(2)
	ds_write_b128 v106, v[86:89] offset:26624
	s_waitcnt vmcnt(1)
	ds_write_b128 v106, v[90:93] offset:12288
	s_waitcnt vmcnt(0)
	ds_write_b128 v106, v[94:97] offset:30720
	s_waitcnt lgkmcnt(0)
	s_barrier
	s_add_u32 s100, s6, 0x27c0000
	s_addc_u32 s101, s7, 0
	v_lshl_add_u64 v[212:213], v[114:115], 0, s[100:101]
	global_load_dwordx4 v[66:69], v[212:213], off offset:128
	v_lshl_add_u64 v[214:215], v[112:113], 0, s[6:7]
	global_load_dwordx4 v[70:73], v[214:215], off offset:128
	s_add_u32 s100, s6, 0x27d0000
	s_addc_u32 s101, s7, 0
	v_lshl_add_u64 v[216:217], v[114:115], 0, s[100:101]
	global_load_dwordx4 v[74:77], v[216:217], off offset:128
	s_add_u32 s100, s6, 0x10000
	s_addc_u32 s101, s7, 0
	v_lshl_add_u64 v[218:219], v[112:113], 0, s[100:101]
	global_load_dwordx4 v[78:81], v[218:219], off offset:128
	s_add_u32 s100, s6, 0x27e0000
	s_addc_u32 s101, s7, 0
	v_lshl_add_u64 v[212:213], v[114:115], 0, s[100:101]
	global_load_dwordx4 v[82:85], v[212:213], off offset:128
	s_add_u32 s100, s6, 0x20000
	s_addc_u32 s101, s7, 0
	v_lshl_add_u64 v[214:215], v[112:113], 0, s[100:101]
	global_load_dwordx4 v[86:89], v[214:215], off offset:128
	s_add_u32 s100, s6, 0x27f0000
	s_addc_u32 s101, s7, 0
	v_lshl_add_u64 v[216:217], v[114:115], 0, s[100:101]
	global_load_dwordx4 v[90:93], v[216:217], off offset:128
	s_add_u32 s100, s6, 0x30000
	s_addc_u32 s101, s7, 0
	v_lshl_add_u64 v[218:219], v[112:113], 0, s[100:101]
	global_load_dwordx4 v[94:97], v[218:219], off offset:128
	ds_read_b128 v[146:149], v121 offset:18432
	ds_read_b128 v[150:153], v120
	ds_read_b128 v[154:157], v248
	ds_read_b128 v[158:161], v249 offset:18432
	ds_read_b128 v[162:165], v121 offset:20480
	ds_read_b128 v[166:169], v249 offset:20480
	ds_read_b128 v[204:207], v121 offset:22528
	ds_read_b128 v[208:211], v249 offset:22528
	ds_read_b128 v[126:129], v121 offset:24576
	ds_read_b128 v[130:133], v249 offset:24576
	s_waitcnt lgkmcnt(8)
	v_mfma_f32_16x16x32_bf16 v[62:65], v[146:149], v[150:153], v[62:65]
	s_waitcnt lgkmcnt(5)
	v_mfma_f32_16x16x32_bf16 v[58:61], v[162:165], v[150:153], v[58:61]
	s_waitcnt lgkmcnt(3)
	v_mfma_f32_16x16x32_bf16 v[54:57], v[204:207], v[150:153], v[54:57]
	s_waitcnt lgkmcnt(1)
	v_mfma_f32_16x16x32_bf16 v[50:53], v[126:129], v[150:153], v[50:53]
	ds_read_b128 v[150:153], v120 offset:2048
	ds_read_b128 v[134:137], v248 offset:2048
	s_waitcnt lgkmcnt(1)
	v_mfma_f32_16x16x32_bf16 v[46:49], v[146:149], v[150:153], v[46:49]
	v_mfma_f32_16x16x32_bf16 v[42:45], v[162:165], v[150:153], v[42:45]
	v_mfma_f32_16x16x32_bf16 v[34:37], v[204:207], v[150:153], v[34:37]
	v_mfma_f32_16x16x32_bf16 v[30:33], v[126:129], v[150:153], v[30:33]
	ds_read_b128 v[150:153], v120 offset:4096
	ds_read_b128 v[138:141], v248 offset:4096
	s_waitcnt lgkmcnt(1)
	v_mfma_f32_16x16x32_bf16 v[18:21], v[146:149], v[150:153], v[18:21]
	v_mfma_f32_16x16x32_bf16 v[14:17], v[162:165], v[150:153], v[14:17]
	v_mfma_f32_16x16x32_bf16 v[10:13], v[204:207], v[150:153], v[10:13]
	v_mfma_f32_16x16x32_bf16 v[6:9], v[126:129], v[150:153], v[6:9]
	ds_read_b128 v[150:153], v120 offset:6144
	ds_read_b128 v[142:145], v248 offset:6144
	s_waitcnt lgkmcnt(1)
	v_mfma_f32_16x16x32_bf16 v[2:5], v[146:149], v[150:153], v[2:5]
	v_mfma_f32_16x16x32_bf16 v[62:65], v[158:161], v[154:157], v[62:65]
	v_mfma_f32_16x16x32_bf16 v[58:61], v[166:169], v[154:157], v[58:61]
	v_mfma_f32_16x16x32_bf16 v[54:57], v[208:211], v[154:157], v[54:57]
	v_mfma_f32_16x16x32_bf16 v[50:53], v[130:133], v[154:157], v[50:53]
	v_mfma_f32_16x16x32_bf16 v[38:41], v[162:165], v[150:153], v[38:41]
	v_mfma_f32_16x16x32_bf16 v[26:29], v[204:207], v[150:153], v[26:29]
	v_mfma_f32_16x16x32_bf16 v[22:25], v[126:129], v[150:153], v[22:25]
	v_mfma_f32_16x16x32_bf16 v[46:49], v[158:161], v[134:137], v[46:49]
	v_mfma_f32_16x16x32_bf16 v[42:45], v[166:169], v[134:137], v[42:45]
	v_mfma_f32_16x16x32_bf16 v[18:21], v[158:161], v[138:141], v[18:21]
	v_mfma_f32_16x16x32_bf16 v[14:17], v[166:169], v[138:141], v[14:17]
	s_waitcnt lgkmcnt(0)
	v_mfma_f32_16x16x32_bf16 v[2:5], v[158:161], v[142:145], v[2:5]
	v_mfma_f32_16x16x32_bf16 v[38:41], v[166:169], v[142:145], v[38:41]
	v_mfma_f32_16x16x32_bf16 v[34:37], v[208:211], v[134:137], v[34:37]
	v_mfma_f32_16x16x32_bf16 v[10:13], v[208:211], v[138:141], v[10:13]
	v_mfma_f32_16x16x32_bf16 v[26:29], v[208:211], v[142:145], v[26:29]
	v_mfma_f32_16x16x32_bf16 v[30:33], v[130:133], v[134:137], v[30:33]
	v_mfma_f32_16x16x32_bf16 v[6:9], v[130:133], v[138:141], v[6:9]
	v_mfma_f32_16x16x32_bf16 v[22:25], v[130:133], v[142:145], v[22:25]
	s_add_u32 s6, s6, 0x80
	s_addc_u32 s7, s7, 0
	s_cmpk_eq_i32 s6, 0x780
	s_cbranch_scc0 .LBB0_792
	s_barrier
	s_waitcnt vmcnt(7)
	ds_write_b128 v106, v[66:69]
	s_waitcnt vmcnt(6)
	ds_write_b128 v106, v[70:73] offset:18432
	s_waitcnt vmcnt(5)
	ds_write_b128 v106, v[74:77] offset:4096
	s_waitcnt vmcnt(4)
	ds_write_b128 v106, v[78:81] offset:22528
	s_waitcnt vmcnt(3)
	ds_write_b128 v106, v[82:85] offset:8192
	s_waitcnt vmcnt(2)
	ds_write_b128 v106, v[86:89] offset:26624
	s_waitcnt vmcnt(1)
	ds_write_b128 v106, v[90:93] offset:12288
	s_waitcnt vmcnt(0)
	ds_write_b128 v106, v[94:97] offset:30720
	s_waitcnt lgkmcnt(0)
	s_barrier
	ds_read_b128 v[66:69], v121 offset:18432
	ds_read_b128 v[70:73], v120
	ds_read_b128 v[74:77], v121 offset:20480
	ds_read_b128 v[78:81], v121 offset:22528
	s_waitcnt lgkmcnt(0)
	v_mfma_f32_16x16x32_bf16 v[82:85], v[78:81], v[70:73], v[54:57]
	s_nop 2
	ds_read_b128 v[54:57], v121 offset:24576
	ds_read_b128 v[90:93], v249 offset:20480
	s_cmp_lt_i32 s20, 2
	v_mfma_f32_16x16x32_bf16 v[62:65], v[66:69], v[70:73], v[62:65]
	ds_read_b128 v[94:97], v249 offset:22528
	s_mov_b64 s[10:11], -1
	v_mfma_f32_16x16x32_bf16 v[58:61], v[74:77], v[70:73], v[58:61]
	s_waitcnt lgkmcnt(2)
	v_mfma_f32_16x16x32_bf16 v[70:73], v[54:57], v[70:73], v[50:53]
	s_nop 2
	ds_read_b128 v[50:53], v120 offset:2048
	s_waitcnt lgkmcnt(0)
	v_mfma_f32_16x16x32_bf16 v[46:49], v[66:69], v[50:53], v[46:49]
	v_mfma_f32_16x16x32_bf16 v[42:45], v[74:77], v[50:53], v[42:45]
	v_mfma_f32_16x16x32_bf16 v[34:37], v[78:81], v[50:53], v[34:37]
	v_mfma_f32_16x16x32_bf16 v[30:33], v[54:57], v[50:53], v[30:33]
	ds_read_b128 v[50:53], v120 offset:4096
	s_waitcnt lgkmcnt(0)
	v_mfma_f32_16x16x32_bf16 v[18:21], v[66:69], v[50:53], v[18:21]
	v_mfma_f32_16x16x32_bf16 v[14:17], v[74:77], v[50:53], v[14:17]
	v_mfma_f32_16x16x32_bf16 v[10:13], v[78:81], v[50:53], v[10:13]
	v_mfma_f32_16x16x32_bf16 v[6:9], v[54:57], v[50:53], v[6:9]
	ds_read_b128 v[50:53], v120 offset:6144
	s_waitcnt lgkmcnt(0)
	v_mfma_f32_16x16x32_bf16 v[2:5], v[66:69], v[50:53], v[2:5]
	v_mfma_f32_16x16x32_bf16 v[66:69], v[74:77], v[50:53], v[38:41]
	v_mfma_f32_16x16x32_bf16 v[74:77], v[78:81], v[50:53], v[26:29]
	ds_read_b128 v[78:81], v249 offset:18432
	v_mfma_f32_16x16x32_bf16 v[86:89], v[54:57], v[50:53], v[22:25]
	s_nop 2
	ds_read_b128 v[22:25], v248
	s_waitcnt lgkmcnt(0)
	v_mfma_f32_16x16x32_bf16 v[54:57], v[90:93], v[22:25], v[58:61]
	v_mfma_f32_16x16x32_bf16 v[58:61], v[94:97], v[22:25], v[82:85]
	s_nop 2
	ds_read_b128 v[82:85], v249 offset:24576
	v_mfma_f32_16x16x32_bf16 v[50:53], v[78:81], v[22:25], v[62:65]
	s_waitcnt lgkmcnt(0)
	v_mfma_f32_16x16x32_bf16 v[62:65], v[82:85], v[22:25], v[70:73]
	ds_read_b128 v[22:25], v248 offset:2048
	s_nop 1
	ds_read_b128 v[70:73], v248 offset:4096
	s_waitcnt lgkmcnt(1)
	v_mfma_f32_16x16x32_bf16 v[46:49], v[78:81], v[22:25], v[46:49]
	v_mfma_f32_16x16x32_bf16 v[42:45], v[90:93], v[22:25], v[42:45]
	v_mfma_f32_16x16x32_bf16 v[38:41], v[94:97], v[22:25], v[34:37]
	v_mfma_f32_16x16x32_bf16 v[34:37], v[82:85], v[22:25], v[30:33]
	s_waitcnt lgkmcnt(0)
	v_mfma_f32_16x16x32_bf16 v[30:33], v[78:81], v[70:73], v[18:21]
	v_mfma_f32_16x16x32_bf16 v[26:29], v[90:93], v[70:73], v[14:17]
	v_mfma_f32_16x16x32_bf16 v[22:25], v[94:97], v[70:73], v[10:13]
	v_mfma_f32_16x16x32_bf16 v[18:21], v[82:85], v[70:73], v[6:9]
	ds_read_b128 v[70:73], v248 offset:6144
	s_waitcnt lgkmcnt(0)
	v_mfma_f32_16x16x32_bf16 v[14:17], v[78:81], v[70:73], v[2:5]
	v_mfma_f32_16x16x32_bf16 v[10:13], v[90:93], v[70:73], v[66:69]
	v_mfma_f32_16x16x32_bf16 v[6:9], v[94:97], v[70:73], v[74:77]
	s_nop 1
	v_or_b32_e32 v66, s9, v117
	v_mfma_f32_16x16x32_bf16 v[2:5], v[82:85], v[70:73], v[86:89]
	s_cbranch_scc1 .LBB0_796
	s_mov_b64 s[10:11], 0
	s_cmp_eq_u32 s20, 2
	s_mov_b64 s[6:7], 0
	s_cbranch_scc0 .LBB0_796
	s_movk_i32 s6, 0x800
	v_cmp_gt_i32_e32 vcc, s6, v66
	s_and_b64 s[6:7], vcc, exec
